# MLA attention: K/V/rope tiles staged global->LDS by LDS-DMA at the top of the tile iteration instead of through registers
# speedup vs baseline: 1.0064x; 1.0064x over previous
; #define AT_GLOADK(kt) do { const size_t r_ = rowbase + (size_t)(kt) * 64; \
;         kreg = *(const u32x4*)(Kp + (r_ + lane) * kpitch + wave * 8); \
;         if (MODE == 0 && wave < 4) kreg2 = *(const u32x4*)(proj + (r_ + lane) * NPROJ + 1920 + wave * 8); } while (0)
; #define AT_GLOADV(kt) do { const size_t r_ = rowbase + (size_t)(kt) * 64; \
;         vreg = *(const u32x4*)(Vp + (r_ + 16 * (wave & 3) + (lane >> 2)) * vpitch + (wave >> 2) * 32 + (lane & 3) * 8); } while (0)
; #define AT_LSTOREK(buf) do { LAS unsigned char* d_ = lds + (buf) * AT_BUF; \
;         *(LAS u32x4*)(d_ + wave * 1024 + lane * 16) = kreg; \
;         if (MODE == 0 && wave < 4) *(LAS u32x4*)(d_ + (8 + wave) * 1024 + lane * 16) = kreg2; } while (0)
; #define AT_LSTOREV(buf) do { LAS unsigned char* d_ = lds + (buf) * AT_BUF; \
;         *(LAS u32x4*)(d_ + AT_V + wave * 1024 + lane * 16) = vreg; } while (0)
; template <int MODE, int NQ>
; __device__ __forceinline__ void attn_unit(LAS unsigned char* lds, const Params& P, int layer, int b, int h, int qb) {
;     ...
;     float mrun[NC], lrun[NC]; f32x16 o[NC][2];
; #pragma unroll
;     for (int cc = 0; cc < NC; ++cc) { mrun[cc] = -1e20f; lrun[cc] = 0.f; o[cc][0] = f32x16{}; o[cc][1] = f32x16{}; }
;     constexpr int NK = NMAP * ND0;
;     const bf16x8 ones8 = (bf16x8){0x3F80, 0x3F80, 0x3F80, 0x3F80, 0x3F80, 0x3F80, 0x3F80, 0x3F80};
;     const bf16x8 zero8 = (bf16x8){0, 0, 0, 0, 0, 0, 0, 0};
;     bf16x8 kf[NK]; s16x4 vlo[4], vhi[4];
;     ...
;     const int vlane = ((lane >> 4) & 1) * 32 + (lane & 3) * 8 + (4 * hi + ((lane & 15) >> 2)) * 64;
;     const int NT = kt1 - kt0, ks = (MODE != 0) ? (q0 / 64 - kt0) : 0;
;     ...
;     AT_GLOADK(AT_TILE(0)); AT_GLOADV(AT_TILE(0)); AT_LSTOREK(0); AT_LSTOREV(0);
;     if (1 < NT) { AT_GLOADK(AT_TILE(1)); AT_GLOADV(AT_TILE(1)); AT_LSTOREK(1); AT_LSTOREV(1); }
;     __syncthreads();
.LBB0_591:
	s_lshl_b32 s1, s8, 8
	s_and_b32 s18, s1, 0x700
	s_lshl_b64 s[8:9], s[14:15], 1
	v_readlane_b32 s1, v252, 16
	s_add_u32 s1, s1, s8
	v_readlane_b32 s10, v252, 17
	s_addc_u32 s10, s10, s9
	s_add_u32 s1, s1, s18
	s_mul_i32 s17, s0, 0x440000
	s_addc_u32 s11, s10, 0
	s_mul_hi_i32 s16, s0, 0x440000
	s_add_u32 s10, s1, s17
	s_addc_u32 s11, s11, s16
	v_mov_b64_e32 v[2:3], s[10:11]
	v_mad_u64_u32 v[226:227], s[10:11], v13, s33, v[2:3]
	v_readlane_b32 s10, v252, 18
	s_add_u32 s8, s10, s8
	v_readlane_b32 s10, v252, 19
	s_mul_hi_i32 s1, s0, 0x840000
	s_mul_i32 s0, s0, 0x840000
	s_addc_u32 s9, s10, s9
	s_add_u32 s0, s8, s0
	s_addc_u32 s1, s9, s1
	v_mov_b64_e32 v[2:3], s[0:1]
	v_mad_u64_u32 v[228:229], s[0:1], v13, s27, v[2:3]
	s_bfe_u32 s0, s7, 0x20006
	s_mul_i32 s0, s0, 0x8800
	s_or_b32 s0, s17, s0
	s_or_b32 s0, s0, s18
	v_mov_b32_e32 v2, s0
	v_mov_b32_e32 v3, s16
	v_lshlrev_b32_e32 v0, 1, v12
	v_mad_u64_u32 v[2:3], s[0:1], v16, s33, v[2:3]
	v_and_b32_e32 v242, 32, v0
	v_lshlrev_b32_e32 v0, 4, v12
	s_lshl_b64 s[0:1], s[22:23], 1
	v_readlane_b32 s7, v252, 20
	v_and_b32_e32 v244, 0xc0, v0
	v_and_b32_e32 v0, 3, v12
	s_add_u32 s0, s7, s0
	v_readlane_b32 s7, v252, 21
	v_lshlrev_b32_e32 v232, 3, v14
	v_lshlrev_b32_e32 v243, 8, v14
	v_lshl_or_b32 v2, v0, 4, v2
	s_addc_u32 s1, s7, s1
	v_mov_b32_e32 v14, v1
	v_mov_b32_e32 v15, v1
	v_lshl_add_u64 v[230:231], s[0:1], 0, v[2:3]
	v_mov_b32_e32 v0, v1
	v_mov_b32_e32 v2, v1
	v_mov_b32_e32 v3, v1
	v_mov_b32_e32 v4, v1
	v_mov_b32_e32 v5, v1
	v_mov_b32_e32 v6, v1
	v_mov_b32_e32 v7, v1
	v_mov_b32_e32 v8, v1
	v_mov_b32_e32 v9, v1
	v_mov_b32_e32 v10, v1
	v_mov_b32_e32 v11, v1
	v_mov_b32_e32 v12, v1
	v_mov_b32_e32 v13, v1
	v_mov_b64_e32 v[30:31], v[14:15]
	v_mov_b64_e32 v[46:47], v[14:15]
	v_mov_b64_e32 v[62:63], v[14:15]
	v_mov_b64_e32 v[78:79], v[14:15]
	s_mov_b32 s7, 0
	v_mov_b32_e32 v245, 0
	v_mov_b32_e32 v112, 0xe0ad78ec
	s_mov_b64 s[0:1], 0
	v_mov_b32_e32 v113, 0xe0ad78ec
	v_mov_b32_e32 v249, 0
	v_mov_b64_e32 v[28:29], v[12:13]
	v_mov_b64_e32 v[26:27], v[10:11]
	v_mov_b64_e32 v[24:25], v[8:9]
	v_mov_b64_e32 v[22:23], v[6:7]
	v_mov_b64_e32 v[20:21], v[4:5]
	v_mov_b64_e32 v[18:19], v[2:3]
	v_mov_b64_e32 v[16:17], v[0:1]
	v_mov_b64_e32 v[44:45], v[12:13]
	v_mov_b64_e32 v[42:43], v[10:11]
	v_mov_b64_e32 v[40:41], v[8:9]
	v_mov_b64_e32 v[38:39], v[6:7]
	v_mov_b64_e32 v[36:37], v[4:5]
	v_mov_b64_e32 v[34:35], v[2:3]
	v_mov_b64_e32 v[32:33], v[0:1]
	v_mov_b64_e32 v[60:61], v[12:13]
	v_mov_b64_e32 v[58:59], v[10:11]
	v_mov_b64_e32 v[56:57], v[8:9]
	v_mov_b64_e32 v[54:55], v[6:7]
	v_mov_b64_e32 v[52:53], v[4:5]
	v_mov_b64_e32 v[50:51], v[2:3]
	v_mov_b64_e32 v[48:49], v[0:1]
	v_mov_b64_e32 v[76:77], v[12:13]
	v_mov_b64_e32 v[74:75], v[10:11]
	v_mov_b64_e32 v[72:73], v[8:9]
	v_mov_b64_e32 v[70:71], v[6:7]
	v_mov_b64_e32 v[68:69], v[4:5]
	v_mov_b64_e32 v[66:67], v[2:3]
	v_mov_b64_e32 v[64:65], v[0:1]
	v_lshl_add_u64 v[2:3], v[226:227], 0, s[0:1]
	v_readfirstlane_b32 s62, v246
	v_lshl_add_u64 v[6:7], v[230:231], 0, s[0:1]
	s_nop 3
	s_add_i32 s62, s62, 0xa000
	s_mov_b32 m0, s62
	s_nop 0
	global_load_lds_dwordx4 v[2:3], off
	s_add_i32 m0, s62, 0x3000
	s_nop 0
	global_load_lds_dwordx4 v[6:7], off
	s_and_b64 vcc, exec, s[40:41]
	s_cbranch_vccnz .LBB0_593
.LBB0_592:
	s_add_i32 m0, s62, 0x2000
	s_nop 0
	global_load_lds_dwordx4 v[228:229], off

; template <int MODE, int NQ>
; __device__ __forceinline__ void attn_unit(LAS unsigned char* lds, const Params& P, int layer, int b, int h, int qb) {
;     ...
;             f32x16 sc[NC];
; #pragma unroll
;             for (int cc = 0; cc < NC; ++cc) {
;                 sc[cc] = f32x16{};
; #pragma unroll
;                 for (int d0 = 0; d0 < ND0; ++d0) sc[cc] = __builtin_amdgcn_mfma_f32_32x32x16_bf16(kf[(cc % NMAP) * ND0 + d0], qf[cc][d0], sc[cc], 0, 0, 0);
;             }
;             __builtin_amdgcn_sched_barrier(0);
;             AT_VLOAD(cur, hf);
;             if (hf == 0) AT_KLOAD(cur, 1); else if (it + 1 < NT) AT_KLOAD(nxt, 0);
;             __builtin_amdgcn_sched_barrier(0);
;             bf16x8 pw[NC][2]; float rmrel[NC]; bool alive = false;
; #pragma unroll
;             for (int cc = 0; cc < NC; ++cc) {
;                 f32x16& s0 = sc[cc];
;                 float mn;
;     ...
;                         for (int r = 0; r < 16; ++r) s0[r] = fast_exp2(s0[r] - mn);
;                     } else {
;                         const float nm = -mn;
; #pragma unroll
;                         for (int r = 0; r < 16; ++r) s0[r] = fast_exp2(__builtin_fmaf(s0[r], c, nm));
;                     }
;                     u32x4 w;
;                     w.x = cvtpk(s0[0], s0[1]); w.y = cvtpk(s0[2], s0[3]); w.z = cvtpk(s0[4], s0[5]); w.w = cvtpk(s0[6], s0[7]); pw[cc][0] = __builtin_bit_cast(bf16x8, w);
;                     w.x = cvtpk(s0[8], s0[9]); w.y = cvtpk(s0[10], s0[11]); w.z = cvtpk(s0[12], s0[13]); w.w = cvtpk(s0[14], s0[15]); pw[cc][1] = __builtin_bit_cast(bf16x8, w);
;                     f32x16 t = __builtin_amdgcn_mfma_f32_32x32x16_bf16(ones8, pw[cc][0], f32x16{}, 0, 0, 0);
;                     t = __builtin_amdgcn_mfma_f32_32x32x16_bf16(ones8, pw[cc][1], t, 0, 0, 0);
;                     lrun[cc] += t[0];
;                 }
;             }
;             if (alive)
; #pragma unroll
;             for (int dv = 0; dv < 2; ++dv)
; #pragma unroll
;                 for (int k2 = 0; k2 < 2; ++k2) {
;                     const s16x4 lo = vlo[dv * 2 + k2], hh = vhi[dv * 2 + k2];
;                     const bf16x8 vf = (bf16x8){lo[0], lo[1], lo[2], lo[3], hh[0], hh[1], hh[2], hh[3]};
; #pragma unroll
;                     for (int cc = 0; cc < NC; ++cc) o[cc][dv] = __builtin_amdgcn_mfma_f32_32x32x16_bf16(vf, pw[cc][k2], o[cc][dv], 0, 0, 0);
;                 }
.LBB0_599:
	v_fma_f32 v80, v80, s97, -v14
	v_exp_f32_e32 v97, v80
	v_fma_f32 v80, v81, s97, -v14
	v_exp_f32_e32 v98, v80
	v_fma_f32 v80, v82, s97, -v14
	v_exp_f32_e32 v99, v80
	v_fma_f32 v80, v83, s97, -v14
	v_exp_f32_e32 v100, v80
	v_fma_f32 v80, v84, s97, -v14
	v_exp_f32_e32 v101, v80
	v_fma_f32 v80, v85, s97, -v14
	v_exp_f32_e32 v102, v80
	v_fma_f32 v80, v86, s97, -v14
	v_exp_f32_e32 v103, v80
	v_fma_f32 v80, v87, s97, -v14
	v_exp_f32_e32 v87, v80
	v_fma_f32 v80, v88, s97, -v14
	v_exp_f32_e32 v88, v80
	v_fma_f32 v80, v89, s97, -v14
	v_exp_f32_e32 v89, v80
	v_fma_f32 v80, v90, s97, -v14
	v_exp_f32_e32 v90, v80
	v_fma_f32 v80, v91, s97, -v14
	v_exp_f32_e32 v91, v80
	v_fma_f32 v80, v92, s97, -v14
	v_exp_f32_e32 v92, v80
	v_fma_f32 v80, v93, s97, -v14
	v_exp_f32_e32 v93, v80
	v_mov_b64_e32 v[82:83], s[62:63]
	v_mov_b64_e32 v[80:81], s[60:61]
	v_cvt_pk_bf16_f32 v84, v97, v98
	v_cvt_pk_bf16_f32 v85, v99, v100
	v_cvt_pk_bf16_f32 v86, v101, v102
	v_cvt_pk_bf16_f32 v87, v103, v87
	s_waitcnt lgkmcnt(12)
	v_mfma_f32_32x32x16_bf16 v[64:79], v[196:199], v[204:207], v[64:79]
	v_fma_f32 v94, v94, s97, -v14
	v_fma_f32 v95, v95, s97, -v14
	v_exp_f32_e32 v94, v94
	v_exp_f32_e32 v95, v95
	v_cvt_pk_bf16_f32 v88, v88, v89
	v_cvt_pk_bf16_f32 v89, v90, v91
	v_cvt_pk_bf16_f32 v90, v92, v93
	v_mfma_f32_32x32x16_bf16 v[98:113], v[80:83], v[84:87], 0
	v_cvt_pk_bf16_f32 v91, v94, v95
	s_add_i32 s8, s7, 1
	s_cmp_lg_u32 s7, 2
	s_cselect_b32 s7, s8, 0
	s_mul_i32 s9, s7, 0x5000
	s_add_i32 s8, s9, 0x5000
	s_cmp_lg_u32 s7, 2
	v_mfma_f32_32x32x16_bf16 v[32:47], v[196:199], v[84:87], v[32:47]
	s_cselect_b32 s8, s8, 0
	s_and_b64 vcc, exec, s[40:41]
	s_waitcnt lgkmcnt(8)
	v_mfma_f32_32x32x16_bf16 v[48:63], v[188:191], v[204:207], v[48:63]
	v_mfma_f32_32x32x16_bf16 v[16:31], v[188:191], v[84:87], v[16:31]
	v_mfma_f32_32x32x16_bf16 v[98:113], v[80:83], v[88:91], v[98:113]
	v_mfma_f32_32x32x16_bf16 v[64:79], v[192:195], v[200:203], v[64:79]
	v_mfma_f32_32x32x16_bf16 v[32:47], v[192:195], v[88:91], v[32:47]
	s_waitcnt lgkmcnt(7)
	v_mfma_f32_32x32x16_bf16 v[48:63], v[184:187], v[200:203], v[48:63]
	v_mfma_f32_32x32x16_bf16 v[16:31], v[184:187], v[88:91], v[16:31]
	s_cbranch_vccnz .LBB0_601
.LBB0_601:
	s_waitcnt lgkmcnt(6)
	v_mfma_f32_32x32x16_bf16 v[100:115], v[180:183], v[160:163], 0
	v_add_f32_e32 v205, v249, v96
	v_mfma_f32_32x32x16_bf16 v[80:95], v[180:183], v[156:159], 0
	s_waitcnt lgkmcnt(5)
	v_mfma_f32_32x32x16_bf16 v[100:115], v[176:179], v[140:143], v[100:115]
	v_mfma_f32_32x32x16_bf16 v[80:95], v[176:179], v[152:155], v[80:95]
	s_waitcnt lgkmcnt(4)
	v_mfma_f32_32x32x16_bf16 v[100:115], v[172:175], v[132:135], v[100:115]
	v_mfma_f32_32x32x16_bf16 v[80:95], v[172:175], v[148:151], v[80:95]
	s_waitcnt lgkmcnt(3)
	v_mfma_f32_32x32x16_bf16 v[100:115], v[168:171], v[128:131], v[100:115]
	v_mfma_f32_32x32x16_bf16 v[80:95], v[168:171], v[144:147], v[80:95]
	s_waitcnt lgkmcnt(2)
	v_mfma_f32_32x32x16_bf16 v[100:115], v[10:13], v[124:127], v[100:115]
	v_mfma_f32_32x32x16_bf16 v[80:95], v[10:13], v[136:139], v[80:95]
	s_waitcnt lgkmcnt(1)
	v_mfma_f32_32x32x16_bf16 v[100:115], v[2:5], v[120:123], v[100:115]
	v_mfma_f32_32x32x16_bf16 v[80:95], v[2:5], v[116:119], v[80:95]
	ds_read_b64_tr_b16 v[196:197], v15 offset:14336
	ds_read_b64_tr_b16 v[198:199], v15 offset:14848
	ds_read_b64_tr_b16 v[192:193], v15 offset:15360
	ds_read_b64_tr_b16 v[194:195], v15 offset:15872
	ds_read_b64_tr_b16 v[10:11], v15 offset:18432
	ds_read_b64_tr_b16 v[12:13], v15 offset:18944
	ds_read_b64_tr_b16 v[2:3], v15 offset:19456
	ds_read_b64_tr_b16 v[4:5], v15 offset:19968
	v_add_u32_e32 v15, s9, v241
	ds_read_b128 v[188:191], v15
	ds_read_b128 v[184:187], v15 offset:2048
	ds_read_b128 v[180:183], v15 offset:4096
	ds_read_b128 v[176:179], v15 offset:6144
	ds_read_b128 v[172:175], v15 offset:8192
	ds_read_b128 v[168:171], v15 offset:10240
	v_max3_f32 v15, v100, s68, v101
	v_max3_f32 v15, v15, v102, v103
	v_max3_f32 v15, v15, v104, v105
	v_max3_f32 v15, v15, v106, v107
	v_max3_f32 v15, v15, v108, v109
	v_max3_f32 v15, v15, v110, v111
	v_max3_f32 v15, v15, v112, v113
	v_max3_f32 v15, v15, v114, v115
	v_mov_b32_e32 v96, v15
	s_nop 1
	v_permlane32_swap_b32_e32 v15, v96
	v_max_f32_e32 v15, v15, v96
	v_mul_f32_e32 v15, 0x3e16c740, v15
	v_max_f32_e32 v15, v0, v15
	v_add_f32_e32 v96, 0x41000000, v0
	v_cmp_gt_f32_e32 vcc, v15, v96
	s_cbranch_vccz .LBB0_603
	v_sub_f32_e32 v0, v0, v15
	v_exp_f32_e32 v0, v0
	v_xor_b32_e32 v96, 0x80000000, v15
	v_mul_f32_e32 v205, v205, v0
	v_pk_mul_f32 v[78:79], v[78:79], v[0:1] op_sel_hi:[1,0]
	v_pk_mul_f32 v[76:77], v[76:77], v[0:1] op_sel_hi:[1,0]
	v_pk_mul_f32 v[74:75], v[74:75], v[0:1] op_sel_hi:[1,0]
	v_pk_mul_f32 v[72:73], v[72:73], v[0:1] op_sel_hi:[1,0]
	v_pk_mul_f32 v[70:71], v[70:71], v[0:1] op_sel_hi:[1,0]
	v_pk_mul_f32 v[68:69], v[68:69], v[0:1] op_sel_hi:[1,0]
	v_pk_mul_f32 v[66:67], v[66:67], v[0:1] op_sel_hi:[1,0]
	v_pk_mul_f32 v[64:65], v[64:65], v[0:1] op_sel_hi:[1,0]
	v_pk_mul_f32 v[62:63], v[62:63], v[0:1] op_sel_hi:[1,0]
	v_pk_mul_f32 v[60:61], v[60:61], v[0:1] op_sel_hi:[1,0]
	v_pk_mul_f32 v[58:59], v[58:59], v[0:1] op_sel_hi:[1,0]
	v_pk_mul_f32 v[56:57], v[56:57], v[0:1] op_sel_hi:[1,0]
	v_pk_mul_f32 v[54:55], v[54:55], v[0:1] op_sel_hi:[1,0]
	v_pk_mul_f32 v[52:53], v[52:53], v[0:1] op_sel_hi:[1,0]
	v_pk_mul_f32 v[50:51], v[50:51], v[0:1] op_sel_hi:[1,0]
	v_pk_mul_f32 v[48:49], v[48:49], v[0:1] op_sel_hi:[1,0]
	v_mov_b32_e32 v0, v15
	s_branch .LBB0_604

; __device__ __forceinline__ unsigned cvtpk(float lo, float hi) { f32x2 v = {lo, hi}; bf16x2_t b = __builtin_convertvector(v, bf16x2_t); return __builtin_bit_cast(unsigned, b); }
; __device__ __forceinline__ float fast_exp2(float x) { return __builtin_amdgcn_exp2f(x); }
; #define AT_LSTOREK(buf) do { LAS unsigned char* d_ = lds + (buf) * AT_BUF; \
;         *(LAS u32x4*)(d_ + wave * 1024 + lane * 16) = kreg; \
;         if (MODE == 0 && wave < 4) *(LAS u32x4*)(d_ + (8 + wave) * 1024 + lane * 16) = kreg2; } while (0)
; template <int MODE, int NQ>
; __device__ __forceinline__ void attn_unit(LAS unsigned char* lds, const Params& P, int layer, int b, int h, int qb) {
;     ...
;                         for (int r = 0; r < 16; ++r) s0[r] = fast_exp2(s0[r] - mn);
;                     } else {
;                         const float nm = -mn;
; #pragma unroll
;                         for (int r = 0; r < 16; ++r) s0[r] = fast_exp2(__builtin_fmaf(s0[r], c, nm));
;                     }
;                     u32x4 w;
;                     w.x = cvtpk(s0[0], s0[1]); w.y = cvtpk(s0[2], s0[3]); w.z = cvtpk(s0[4], s0[5]); w.w = cvtpk(s0[6], s0[7]); pw[cc][0] = __builtin_bit_cast(bf16x8, w);
;                     w.x = cvtpk(s0[8], s0[9]); w.y = cvtpk(s0[10], s0[11]); w.z = cvtpk(s0[12], s0[13]); w.w = cvtpk(s0[14], s0[15]); pw[cc][1] = __builtin_bit_cast(bf16x8, w);
;                     f32x16 t = __builtin_amdgcn_mfma_f32_32x32x16_bf16(ones8, pw[cc][0], f32x16{}, 0, 0, 0);
;                     t = __builtin_amdgcn_mfma_f32_32x32x16_bf16(ones8, pw[cc][1], t, 0, 0, 0);
;                     lrun[cc] += t[0];
;                 }
;             }
;             if (alive)
; #pragma unroll
;             for (int dv = 0; dv < 2; ++dv)
; #pragma unroll
;                 for (int k2 = 0; k2 < 2; ++k2) {
;                     const s16x4 lo = vlo[dv * 2 + k2], hh = vhi[dv * 2 + k2];
;                     const bf16x8 vf = (bf16x8){lo[0], lo[1], lo[2], lo[3], hh[0], hh[1], hh[2], hh[3]};
; #pragma unroll
;                     for (int cc = 0; cc < NC; ++cc) o[cc][dv] = __builtin_amdgcn_mfma_f32_32x32x16_bf16(vf, pw[cc][k2], o[cc][dv], 0, 0, 0);
;                 }
;             if (it + 2 < NT) { if (hf == 0) AT_LSTOREK(bn2); else AT_LSTOREV(bn2); }
;         }
;         __syncthreads();
.LBB0_607:
	v_fmamk_f32 v80, v80, 0x3e16c740, v98
	v_fmamk_f32 v81, v81, 0x3e16c740, v98
	v_fmamk_f32 v82, v82, 0x3e16c740, v98
	v_fmamk_f32 v83, v83, 0x3e16c740, v98
	v_fmamk_f32 v84, v84, 0x3e16c740, v98
	v_fmamk_f32 v85, v85, 0x3e16c740, v98
	v_fmamk_f32 v86, v86, 0x3e16c740, v98
	v_fmamk_f32 v87, v87, 0x3e16c740, v98
	v_mov_b64_e32 v[106:107], s[62:63]
	v_exp_f32_e32 v80, v80
	v_exp_f32_e32 v81, v81
	v_exp_f32_e32 v82, v82
	v_exp_f32_e32 v83, v83
	v_exp_f32_e32 v84, v84
	v_exp_f32_e32 v85, v85
	v_exp_f32_e32 v86, v86
	v_exp_f32_e32 v87, v87
	v_fmamk_f32 v88, v88, 0x3e16c740, v98
	v_fmamk_f32 v89, v89, 0x3e16c740, v98
	v_fmamk_f32 v90, v90, 0x3e16c740, v98
	v_fmamk_f32 v91, v91, 0x3e16c740, v98
	v_fmamk_f32 v92, v92, 0x3e16c740, v98
	v_fmamk_f32 v93, v93, 0x3e16c740, v98
	v_fmamk_f32 v94, v94, 0x3e16c740, v98
	v_fmac_f32_e32 v98, 0x3e16c740, v95
	v_mov_b64_e32 v[104:105], s[60:61]
	v_exp_f32_e32 v88, v88
	v_exp_f32_e32 v89, v89
	v_exp_f32_e32 v90, v90
	v_exp_f32_e32 v91, v91
	v_exp_f32_e32 v92, v92
	v_exp_f32_e32 v93, v93
	v_exp_f32_e32 v94, v94
	v_exp_f32_e32 v95, v98
	v_add_f32_e32 v249, v205, v96
	v_cvt_pk_bf16_f32 v96, v80, v81
	v_cvt_pk_bf16_f32 v97, v82, v83
	v_cvt_pk_bf16_f32 v98, v84, v85
	v_cvt_pk_bf16_f32 v99, v86, v87
	v_cvt_pk_bf16_f32 v100, v88, v89
	v_cvt_pk_bf16_f32 v101, v90, v91
	v_cvt_pk_bf16_f32 v102, v92, v93
	v_cvt_pk_bf16_f32 v103, v94, v95
	v_mfma_f32_32x32x16_bf16 v[80:95], v[104:107], v[96:99], 0
	s_add_u32 s0, s0, 0x22000
	s_addc_u32 s1, s1, 0
	s_mov_b64 s[10:11], 0x42000
	v_lshl_add_u64 v[228:229], v[228:229], 0, s[10:11]
	s_cmp_eq_u32 s0, 0x3fc000
	s_waitcnt vmcnt(0)
	s_waitcnt lgkmcnt(0)
	v_mfma_f32_32x32x16_bf16 v[64:79], v[196:199], v[112:115], v[64:79]
	s_barrier
	v_mfma_f32_32x32x16_bf16 v[32:47], v[196:199], v[96:99], v[32:47]
	v_mfma_f32_32x32x16_bf16 v[48:63], v[10:13], v[112:115], v[48:63]
	v_mfma_f32_32x32x16_bf16 v[16:31], v[10:13], v[96:99], v[16:31]
	v_mfma_f32_32x32x16_bf16 v[80:95], v[104:107], v[100:103], v[80:95]
	v_mfma_f32_32x32x16_bf16 v[64:79], v[192:195], v[200:203], v[64:79]
	s_nop 10
	v_add_f32_e32 v245, v15, v80
	v_mfma_f32_32x32x16_bf16 v[32:47], v[192:195], v[100:103], v[32:47]
	v_mfma_f32_32x32x16_bf16 v[48:63], v[2:5], v[200:203], v[48:63]
	v_mfma_f32_32x32x16_bf16 v[16:31], v[2:5], v[100:103], v[16:31]
	s_cbranch_scc1 .LBB0_609
	v_mov_b32_e32 v112, v14
	v_mov_b32_e32 v113, v0
	v_lshl_add_u64 v[2:3], v[226:227], 0, s[0:1]
	v_readfirstlane_b32 s62, v246
	v_lshl_add_u64 v[6:7], v[230:231], 0, s[0:1]
	s_sub_i32 s63, 0xf000, s9
	s_sub_i32 s63, s63, s8
	s_nop 1
	s_add_i32 s62, s62, s63
	s_mov_b32 m0, s62
	s_nop 0
	global_load_lds_dwordx4 v[2:3], off
	s_add_i32 m0, s62, 0x3000
	s_nop 0
	global_load_lds_dwordx4 v[6:7], off
	s_and_b64 vcc, exec, s[40:41]
	s_cbranch_vccz .LBB0_592
	s_branch .LBB0_593
